# v13: v12 + FFN-norm modulation-vector loads hoisted above the first wait (one wait per row instead of four)
# speedup vs baseline: 1.0207x; 1.0027x over previous
.LBB0_1621:
	s_or_b64 exec, exec, s[12:13]
	v_mov_b32_e32 v16, 0xffff8000
	v_cndmask_b32_e64 v16, v16, 0, vcc
	v_mov_b32_e32 v17, s3
	v_mov_b32_e32 v18, s7
	v_add_u32_e32 v16, v16, v36
	v_cndmask_b32_e32 v19, v17, v18, vcc
	v_mov_b32_e32 v17, s2
	v_mov_b32_e32 v18, s6
	v_cndmask_b32_e32 v18, v17, v18, vcc
	v_ashrrev_i32_e32 v17, 31, v16
	v_lshlrev_b64 v[16:17], 12, v[16:17]
	v_lshl_add_u64 v[16:17], v[18:19], 0, v[16:17]
	v_lshl_add_u64 v[16:17], v[16:17], 0, v[112:113]
	global_load_dwordx4 v[28:31], v[16:17], off nt
	global_load_dwordx4 v[24:27], v[16:17], off offset:1024 nt
	global_load_dwordx4 v[20:23], v[16:17], off offset:2048 nt
	s_nop 0
	global_load_dwordx4 v[16:19], v[16:17], off offset:3072 nt
	v_readlane_b32 s12, v255, 25
	v_readlane_b32 s13, v255, 26
	v_mov_b32_e32 v41, v113
	v_mov_b32_e32 v45, v113
	v_lshl_add_u64 v[32:33], v[32:33], 2, s[12:13]
	s_mov_b64 s[12:13], 0x4000
	v_lshl_add_u64 v[114:115], v[32:33], 0, s[12:13]
	v_lshl_add_u64 v[116:117], v[32:33], 0, s[24:25]
	v_lshl_add_u64 v[114:115], v[114:115], 0, v[112:113]
	v_lshl_add_u64 v[116:117], v[116:117], 0, v[112:113]
	global_load_dwordx4 v[80:83], v[114:115], off
	global_load_dwordx4 v[84:87], v[116:117], off
	global_load_dwordx4 v[88:91], v[114:115], off offset:1024
	global_load_dwordx4 v[92:95], v[116:117], off offset:1024
	global_load_dwordx4 v[96:99], v[114:115], off offset:2048
	global_load_dwordx4 v[100:103], v[116:117], off offset:2048
	global_load_dwordx4 v[104:107], v[114:115], off offset:3072
	global_load_dwordx4 v[108:111], v[116:117], off offset:3072
	s_waitcnt vmcnt(0)
	v_lshl_add_u64 v[48:49], v[32:33], 0, s[12:13]
	v_lshl_add_u64 v[34:35], v[48:49], 0, v[112:113]
	v_lshl_add_u64 v[50:51], v[32:33], 0, s[24:25]
	v_mov_b64_e32 v[52:53], v[80:81]
	v_mov_b64_e32 v[54:55], v[82:83]
	v_lshl_add_u64 v[32:33], v[50:51], 0, v[112:113]
	v_mov_b64_e32 v[32:33], v[84:85]
	v_mov_b64_e32 v[34:35], v[86:87]
	v_add_u32_e32 v36, s30, v36
	s_waitcnt lgkmcnt(0)
	v_mov_b32_e32 v56, v29
	v_mov_b32_e32 v57, v25
	v_mov_b32_e32 v46, v28
	v_mov_b32_e32 v47, v24
	v_pk_mul_f32 v[56:57], v[56:57], v[56:57]
	v_mov_b32_e32 v58, v20
	v_pk_fma_f32 v[46:47], v[46:47], v[46:47], v[56:57]
	v_mov_b32_e32 v56, v21
	v_mov_b32_e32 v57, v17
	v_mov_b32_e32 v59, v16
	v_pk_mul_f32 v[56:57], v[56:57], v[56:57]
	s_waitcnt vmcnt(0)
	v_pk_add_f32 v[60:61], v[54:55], 1.0 op_sel_hi:[1,0]
	v_pk_fma_f32 v[56:57], v[58:59], v[58:59], v[56:57]
	v_mov_b32_e32 v58, v30
	v_mov_b32_e32 v59, v26
	v_pk_fma_f32 v[46:47], v[58:59], v[58:59], v[46:47]
	v_mov_b32_e32 v58, v22
	v_mov_b32_e32 v59, v18
	v_pk_fma_f32 v[56:57], v[58:59], v[58:59], v[56:57]
	v_mov_b32_e32 v58, v31
	v_mov_b32_e32 v59, v27
	v_pk_fma_f32 v[46:47], v[58:59], v[58:59], v[46:47]
	v_mov_b32_e32 v58, v23
	v_mov_b32_e32 v59, v19
	v_pk_fma_f32 v[56:57], v[58:59], v[58:59], v[56:57]
	v_add_f32_e32 v37, v46, v47
	v_add_f32_e32 v37, v37, v56
	v_add_f32_e32 v37, v37, v57
	v_lshl_add_u64 v[56:57], v[48:49], 0, v[40:41]
	v_pk_add_f32 v[58:59], v[52:53], 1.0 op_sel_hi:[1,0]
	v_add_f32_dpp v37, v37, v37 quad_perm:[1,0,3,2] row_mask:0xf bank_mask:0xf bound_ctrl:1
	v_mov_b64_e32 v[52:53], v[88:89]
	v_mov_b64_e32 v[54:55], v[90:91]
	s_nop 0
	v_add_f32_dpp v37, v37, v37 quad_perm:[2,3,0,1] row_mask:0xf bank_mask:0xf bound_ctrl:1
	s_nop 1
	v_add_f32_dpp v37, v37, v37 row_half_mirror row_mask:0xf bank_mask:0xf bound_ctrl:1
	s_nop 1
	v_add_f32_dpp v37, v37, v37 row_mirror row_mask:0xf bank_mask:0xf bound_ctrl:1
	s_nop 0
	v_readlane_b32 s14, v37, 16
	v_readlane_b32 s15, v37, 48
	v_readlane_b32 s12, v37, 0
	v_readlane_b32 s13, v37, 32
	v_mov_b32_e32 v46, s14
	v_mov_b32_e32 v47, s15
	v_pk_add_f32 v[46:47], s[12:13], v[46:47]
	v_readlane_b32 s12, v254, 21
	v_add_f32_e32 v37, v46, v47
	v_fmamk_f32 v37, v37, 0x3a800000, v248
	v_mul_f32_e32 v43, 0x4b800000, v37
	v_cmp_gt_f32_e32 vcc, s77, v37
	v_readlane_b32 s13, v254, 22
	s_nop 0
	v_cndmask_b32_e32 v37, v37, v43, vcc
	v_rsq_f32_e32 v37, v37
	s_nop 0
	v_mul_f32_e32 v43, 0x45800000, v37
	v_cndmask_b32_e32 v46, v37, v43, vcc
	v_pk_mul_f32 v[28:29], v[28:29], v[46:47] op_sel_hi:[1,0]
	v_pk_mul_f32 v[30:31], v[30:31], v[46:47] op_sel_hi:[1,0]
	v_pk_mul_f32 v[28:29], v[0:1], v[28:29]
	v_pk_mul_f32 v[30:31], v[2:3], v[30:31]
	v_pk_fma_f32 v[28:29], v[58:59], v[28:29], v[32:33]
	v_lshl_add_u64 v[32:33], v[50:51], 0, v[40:41]
	v_pk_fma_f32 v[30:31], v[60:61], v[30:31], v[34:35]
	v_mov_b64_e32 v[32:33], v[92:93]
	v_mov_b64_e32 v[34:35], v[94:95]
	v_mov_b32_e32 v43, v113
	v_pk_mul_f32 v[24:25], v[24:25], v[46:47] op_sel_hi:[1,0]
	v_lshl_add_u64 v[56:57], v[48:49], 0, v[42:43]
	v_pk_mul_f32 v[26:27], v[26:27], v[46:47] op_sel_hi:[1,0]
	v_pk_mul_f32 v[24:25], v[4:5], v[24:25]
	v_pk_mul_f32 v[26:27], v[6:7], v[26:27]
	v_lshl_add_u64 v[48:49], v[48:49], 0, v[44:45]
	v_pk_mul_f32 v[16:17], v[16:17], v[46:47] op_sel_hi:[1,0]
	v_pk_mul_f32 v[18:19], v[18:19], v[46:47] op_sel_hi:[1,0]
	v_pk_mul_f32 v[16:17], v[12:13], v[16:17]
	v_pk_mul_f32 v[18:19], v[14:15], v[18:19]
	v_cvt_pk_bf16_f32 v28, v28, v29
	v_cvt_pk_bf16_f32 v29, v30, v31
	v_cmp_le_i32_e32 vcc, s40, v36
	s_or_b64 s[10:11], vcc, s[10:11]
	s_waitcnt vmcnt(0) lgkmcnt(0)
	v_pk_add_f32 v[58:59], v[52:53], 1.0 op_sel_hi:[1,0]
	v_pk_add_f32 v[60:61], v[54:55], 1.0 op_sel_hi:[1,0]
	v_mov_b64_e32 v[52:53], v[96:97]
	v_mov_b64_e32 v[54:55], v[98:99]
	v_pk_mul_f32 v[56:57], v[20:21], v[46:47] op_sel_hi:[1,0]
	v_pk_fma_f32 v[24:25], v[58:59], v[24:25], v[32:33]
	v_lshl_add_u64 v[32:33], v[50:51], 0, v[42:43]
	v_lshl_add_u64 v[50:51], v[50:51], 0, v[44:45]
	v_pk_fma_f32 v[26:27], v[60:61], v[26:27], v[34:35]
	v_mov_b64_e32 v[32:33], v[100:101]
	v_mov_b64_e32 v[34:35], v[102:103]
	v_pk_mul_f32 v[58:59], v[22:23], v[46:47] op_sel_hi:[1,0]
	v_mov_b64_e32 v[20:21], v[104:105]
	v_mov_b64_e32 v[22:23], v[106:107]
	s_nop 0
	v_mov_b64_e32 v[48:49], v[108:109]
	v_mov_b64_e32 v[50:51], v[110:111]
	v_pk_mul_f32 v[56:57], v[8:9], v[56:57]
	v_pk_mul_f32 v[58:59], v[10:11], v[58:59]
	v_cvt_pk_bf16_f32 v24, v24, v25
	v_cvt_pk_bf16_f32 v25, v26, v27
	s_waitcnt vmcnt(0) lgkmcnt(0)
	v_pk_add_f32 v[52:53], v[52:53], 1.0 op_sel_hi:[1,0]
	v_pk_add_f32 v[54:55], v[54:55], 1.0 op_sel_hi:[1,0]
	v_pk_fma_f32 v[32:33], v[52:53], v[56:57], v[32:33]
	v_pk_add_f32 v[20:21], v[20:21], 1.0 op_sel_hi:[1,0]
	v_pk_fma_f32 v[34:35], v[54:55], v[58:59], v[34:35]
	v_pk_fma_f32 v[16:17], v[20:21], v[16:17], v[48:49]
	v_pk_add_f32 v[20:21], v[22:23], 1.0 op_sel_hi:[1,0]
	v_cvt_pk_bf16_f32 v16, v16, v17
	v_pk_fma_f32 v[18:19], v[20:21], v[18:19], v[50:51]
	v_cvt_pk_bf16_f32 v26, v32, v33
	v_cvt_pk_bf16_f32 v17, v18, v19
	v_cvt_pk_bf16_f32 v27, v34, v35
	global_store_dwordx2 v[38:39], v[28:29], off
	global_store_dwordx2 v[38:39], v[24:25], off offset:512
	global_store_dwordx2 v[38:39], v[26:27], off offset:1024
	global_store_dwordx2 v[38:39], v[16:17], off offset:1536
	v_lshl_add_u64 v[38:39], v[38:39], 0, s[12:13]
	s_andn2_b64 exec, exec, s[10:11]
	s_cbranch_execz .LBB0_1624
